# grid barrier: the 16th of 32 local arrivers issues one early L2 writeback per XCD so the XCD leader's release writeback has less to flush
# baseline (speedup 1.0000x reference)
.LBB0_192:
	s_or_b64 exec, exec, s[10:11]
	v_cvt_f32_u32_e32 v5, v3
	s_waitcnt vmcnt(0)
	v_readfirstlane_b32 s2, v4
	v_sub_u32_e32 v4, 0, v3
	v_rcp_iflag_f32_e32 v5, v5
	v_add_u32_e32 v6, s2, v0
	v_mul_f32_e32 v5, 0x4f7ffffe, v5
	v_cvt_u32_f32_e32 v5, v5
	v_mul_lo_u32 v0, v4, v5
	v_mul_hi_u32 v0, v5, v0
	v_add_u32_e32 v0, v5, v0
	v_mul_hi_u32 v0, v6, v0
	v_mul_lo_u32 v4, v0, v3
	v_sub_u32_e32 v4, v6, v4
	v_add_u32_e32 v5, 1, v0
	v_cmp_ge_u32_e32 vcc, v4, v3
	s_nop 1
	v_cndmask_b32_e32 v0, v0, v5, vcc
	v_sub_u32_e32 v5, v4, v3
	v_cndmask_b32_e32 v4, v4, v5, vcc
	v_add_u32_e32 v5, 1, v0
	v_cmp_ge_u32_e32 vcc, v4, v3
	v_add_u32_e32 v4, 1, v6
	s_nop 0
	v_cndmask_b32_e32 v0, v0, v5, vcc
	v_mul_lo_u32 v5, v3, v0
	v_add_u32_e32 v3, v5, v3
	v_cmp_ne_u32_e32 vcc, v4, v3
	s_and_saveexec_b64 s[6:7], vcc
	s_xor_b64 s[10:11], exec, s[6:7]
	s_cbranch_execz .LBB0_206
	v_sub_u32_e32 v4, v3, v5
	v_sub_u32_e32 v6, v6, v5
	v_lshrrev_b32_e32 v4, 1, v4
	v_cmp_eq_u32_e32 vcc, v6, v4
	s_cbranch_vccz .Lxb_noearly
	buffer_wbl2 sc1
.Lxb_noearly:
	v_readlane_b32 s6, v254, 52
	v_readlane_b32 s7, v254, 53
	s_waitcnt lgkmcnt(0)
	s_nop 3
	global_load_dword v2, v1, s[6:7] sc1
	s_waitcnt vmcnt(0)
	v_cmp_eq_u32_e32 vcc, v2, v0
	s_and_saveexec_b64 s[18:19], vcc
	s_cbranch_execz .LBB0_205
	s_mov_b32 s2, 1
	s_mov_b64 s[20:21], 0
	s_branch .LBB0_196
